# sc1 epilogue stores only in the last HB / mixer-B unit of each workgroup (runtime-selected)
# baseline (speedup 1.0000x reference)
.LBB0_185:
	s_cmp_lg_u64 s[36:37], 0
	s_cselect_b32 s32, 1, 0
	v_lshl_add_u32 v154, s86, 8, v139
	v_ashrrev_i32_e32 v155, 31, v154
	v_lshl_add_u32 v136, s11, 7, v157
	v_lshlrev_b64 v[152:153], 11, v[154:155]
	v_lshl_add_u64 v[152:153], s[50:51], 0, v[152:153]
	v_lshlrev_b64 v[166:167], 1, v[136:137]
	v_pk_mul_f32 v[162:163], v[124:125], v[116:117]
	v_lshl_add_u64 v[152:153], v[152:153], 0, v[166:167]
	v_pk_mul_f32 v[164:165], v[126:127], v[118:119]
	v_cvt_pk_bf16_f32 v162, v162, v163
	v_pk_mul_f32 v[168:169], v[122:123], v[114:115]
	v_pk_mul_f32 v[170:171], v[120:121], v[112:113]
	v_cvt_pk_bf16_f32 v163, v164, v165
	v_pk_mul_f32 v[172:173], v[104:105], v[96:97]
	v_cvt_pk_bf16_f32 v164, v170, v171
	v_cvt_pk_bf16_f32 v165, v168, v169
	s_cmp_lg_u32 s32, 0
	s_cbranch_scc1 .Lls_hb0_w
	global_store_dwordx4 v[152:153], v[162:165], off
	s_branch .Lls_hb0_j
.Lls_hb0_w:
	global_store_dwordx4 v[152:153], v[162:165], off sc1
.Lls_hb0_j:
	v_pk_mul_f32 v[170:171], v[106:107], v[98:99]
	s_mov_b32 s0, 0x40000
	v_or_b32_e32 v162, 16, v154
	v_ashrrev_i32_e32 v163, 31, v162
	v_lshlrev_b64 v[162:163], 11, v[162:163]
	v_lshl_add_u64 v[162:163], s[50:51], 0, v[162:163]
	v_lshl_add_u64 v[168:169], v[162:163], 0, v[166:167]
	v_pk_mul_f32 v[162:163], v[108:109], v[100:101]
	v_pk_mul_f32 v[164:165], v[110:111], v[102:103]
	v_cvt_pk_bf16_f32 v162, v162, v163
	s_nop 0
	v_cvt_pk_bf16_f32 v163, v164, v165
	v_cvt_pk_bf16_f32 v164, v172, v173
	v_cvt_pk_bf16_f32 v165, v170, v171
	s_cmp_lg_u32 s32, 0
	s_cbranch_scc1 .Lls_hb1_w
	global_store_dwordx4 v[168:169], v[162:165], off
	s_branch .Lls_hb1_j
.Lls_hb1_w:
	global_store_dwordx4 v[168:169], v[162:165], off sc1
.Lls_hb1_j:
	v_pk_mul_f32 v[170:171], v[90:91], v[82:83]
	v_pk_mul_f32 v[172:173], v[88:89], v[80:81]
	v_or_b32_e32 v162, 32, v154
	v_ashrrev_i32_e32 v163, 31, v162
	v_lshlrev_b64 v[162:163], 11, v[162:163]
	v_lshl_add_u64 v[162:163], s[50:51], 0, v[162:163]
	v_or_b32_e32 v154, 48, v154
	v_lshl_add_u64 v[168:169], v[162:163], 0, v[166:167]
	v_pk_mul_f32 v[162:163], v[92:93], v[84:85]
	v_ashrrev_i32_e32 v155, 31, v154
	v_pk_mul_f32 v[164:165], v[94:95], v[86:87]
	v_cvt_pk_bf16_f32 v162, v162, v163
	v_lshlrev_b64 v[154:155], 11, v[154:155]
	v_cvt_pk_bf16_f32 v163, v164, v165
	v_cvt_pk_bf16_f32 v164, v172, v173
	v_cvt_pk_bf16_f32 v165, v170, v171
	s_cmp_lg_u32 s32, 0
	s_cbranch_scc1 .Lls_hb2_w
	global_store_dwordx4 v[168:169], v[162:165], off
	s_branch .Lls_hb2_j

.Lls_hb2_j:
	v_lshl_add_u64 v[154:155], s[50:51], 0, v[154:155]
	v_lshl_add_u64 v[154:155], v[154:155], 0, v[166:167]
	v_pk_mul_f32 v[162:163], v[76:77], v[68:69]
	v_pk_mul_f32 v[164:165], v[78:79], v[70:71]
	v_cvt_pk_bf16_f32 v162, v162, v163
	v_pk_mul_f32 v[166:167], v[74:75], v[66:67]
	v_cvt_pk_bf16_f32 v163, v164, v165
	v_pk_mul_f32 v[168:169], v[72:73], v[64:65]
	s_nop 0
	v_cvt_pk_bf16_f32 v164, v168, v169
	v_cvt_pk_bf16_f32 v165, v166, v167
	s_cmp_lg_u32 s32, 0
	s_cbranch_scc1 .Lls_hb3_w
	global_store_dwordx4 v[154:155], v[162:165], off
	s_branch .Lls_hb3_j
.Lls_hb3_w:
	global_store_dwordx4 v[154:155], v[162:165], off sc1
.Lls_hb3_j:
	v_pk_mul_f32 v[154:155], v[62:63], v[54:55]
	v_pk_mul_f32 v[166:167], v[58:59], v[50:51]
	v_pk_mul_f32 v[162:163], v[60:61], v[52:53]
	v_pk_mul_f32 v[164:165], v[56:57], v[48:49]
	v_cvt_pk_bf16_f32 v162, v162, v163
	v_cvt_pk_bf16_f32 v163, v154, v155
	v_add_co_u32_e32 v154, vcc, s0, v152
	v_cvt_pk_bf16_f32 v164, v164, v165
	v_cvt_pk_bf16_f32 v165, v166, v167
	s_mov_b32 s0, 0x48000
	s_nop 0
	v_addc_co_u32_e32 v155, vcc, 0, v153, vcc
	s_cmp_lg_u32 s32, 0
	s_cbranch_scc1 .Lls_hb4_w
	global_store_dwordx4 v[154:155], v[162:165], off
	s_branch .Lls_hb4_j

.Lls_hb4_j:
	v_pk_mul_f32 v[154:155], v[46:47], v[38:39]
	v_pk_mul_f32 v[166:167], v[42:43], v[34:35]
	v_pk_mul_f32 v[162:163], v[44:45], v[36:37]
	v_pk_mul_f32 v[164:165], v[40:41], v[32:33]
	v_cvt_pk_bf16_f32 v162, v162, v163
	v_cvt_pk_bf16_f32 v163, v154, v155
	v_add_co_u32_e32 v154, vcc, s0, v152
	v_cvt_pk_bf16_f32 v164, v164, v165
	v_cvt_pk_bf16_f32 v165, v166, v167
	s_mov_b32 s0, 0x50000
	s_nop 0
	v_addc_co_u32_e32 v155, vcc, 0, v153, vcc
	s_cmp_lg_u32 s32, 0
	s_cbranch_scc1 .Lls_hb5_w
	global_store_dwordx4 v[154:155], v[162:165], off
	s_branch .Lls_hb5_j

.Lls_hb5_j:
	v_pk_mul_f32 v[154:155], v[30:31], v[22:23]
	v_pk_mul_f32 v[166:167], v[26:27], v[18:19]
	v_pk_mul_f32 v[162:163], v[28:29], v[20:21]
	v_pk_mul_f32 v[164:165], v[24:25], v[16:17]
	v_cvt_pk_bf16_f32 v162, v162, v163
	v_cvt_pk_bf16_f32 v163, v154, v155
	v_add_co_u32_e32 v154, vcc, s0, v152
	v_cvt_pk_bf16_f32 v164, v164, v165
	v_cvt_pk_bf16_f32 v165, v166, v167
	v_pk_mul_f32 v[166:167], v[10:11], v[2:3]
	s_nop 0
	v_addc_co_u32_e32 v155, vcc, 0, v153, vcc
	v_add_co_u32_e32 v152, vcc, 0x58000, v152
	s_cmp_lg_u32 s32, 0
	s_cbranch_scc1 .Lls_hb6_w
	global_store_dwordx4 v[154:155], v[162:165], off
	s_branch .Lls_hb6_j

.Lls_hb6_j:
	s_nop 0
	v_addc_co_u32_e32 v153, vcc, 0, v153, vcc
	v_pk_mul_f32 v[162:163], v[12:13], v[4:5]
	v_pk_mul_f32 v[164:165], v[8:9], v[0:1]
	v_pk_mul_f32 v[154:155], v[14:15], v[6:7]
	v_cvt_pk_bf16_f32 v162, v162, v163
	s_nop 0
	v_cvt_pk_bf16_f32 v163, v154, v155
	v_cvt_pk_bf16_f32 v164, v164, v165
	v_cvt_pk_bf16_f32 v165, v166, v167
	s_cmp_lg_u32 s32, 0
	s_cbranch_scc1 .Lls_hb7_w
	global_store_dwordx4 v[152:153], v[162:165], off
	s_branch .Lls_hb7_j

.Lls_hb7_j:
	s_cbranch_execnz .LBB0_190

.LBB0_312:
	s_cmp_eq_u64 s[6:7], 0
	s_cselect_b32 s32, 1, 0
	v_add_u32_e32 v210, s87, v237
	v_lshlrev_b64 v[112:113], 2, v[210:211]
	v_lshl_add_u64 v[116:117], s[60:61], 0, v[112:113]
	v_lshl_add_u64 v[140:141], s[34:35], 0, v[112:113]
	v_lshl_add_u64 v[144:145], s[36:37], 0, v[112:113]
	global_load_dwordx4 v[112:115], v[116:117], off offset:16
	global_load_dwordx4 v[136:139], v[116:117], off
	s_nop 0
	global_load_dwordx4 v[116:119], v[140:141], off offset:16
	s_nop 0
	global_load_dwordx4 v[140:143], v[140:141], off
	s_nop 0
	global_load_dwordx4 v[148:151], v[144:145], off offset:16
	global_load_dwordx4 v[152:155], v[144:145], off
	s_lshl_b32 s11, s94, 8
	s_add_i32 s11, s11, s77
	s_and_b32 s8, s11, 0x7c0
	s_cmp_lg_u32 s8, 0
	s_cselect_b64 s[16:17], -1, 0
	s_xor_b64 s[8:9], s[0:1], -1
	s_and_b64 s[16:17], s[8:9], s[16:17]
	v_mov_b32_e32 v156, 0
	v_mov_b32_e32 v157, 0
	v_mov_b32_e32 v158, 0
	v_mov_b32_e32 v159, 0
	s_and_saveexec_b64 s[40:41], s[16:17]
	s_cbranch_execz .LBB0_314
	v_add_u32_e32 v144, s11, v238
	v_ashrrev_i32_e32 v145, 31, v144
	v_lshlrev_b64 v[144:145], 11, v[144:145]
	v_lshl_add_u64 v[144:145], s[50:51], 0, v[144:145]
	v_lshl_add_u64 v[144:145], v[210:211], 1, v[144:145]
	global_load_dwordx4 v[156:159], v[144:145], off
.LBB0_314:
	s_or_b64 exec, exec, s[40:41]
	v_or_b32_e32 v187, s11, v233
	v_lshlrev_b32_e32 v187, 11, v187
	v_lshl_add_u32 v187, v210, 1, v187
	v_mov_b32_e32 v250, 0
	v_mov_b32_e32 v251, 0
	v_mov_b32_e32 v252, 0
	v_mov_b32_e32 v253, 0
	s_mov_b64 s[40:41], exec
	s_and_b64 exec, exec, s[8:9]
	v_add_u32_e32 v187, 0x38000, v187
	s_nop 0
	global_load_dwordx4 v[250:253], v187, s[50:51]
	v_add_u32_e32 v187, 0xfffc8000, v187
	s_mov_b64 exec, s[40:41]
	global_load_dwordx4 v[188:191], v187, s[50:51]
	v_add_u32_e32 v187, 0x8000, v187
	global_load_dwordx4 v[192:195], v187, s[50:51]
	v_add_u32_e32 v187, 0x8000, v187
	global_load_dwordx4 v[196:199], v187, s[50:51]
	v_add_u32_e32 v187, 0x8000, v187
	global_load_dwordx4 v[228:231], v187, s[50:51]
	v_add_u32_e32 v187, 0x28000, v187
	global_load_dwordx4 v[246:249], v187, s[50:51]
	v_mul_f32_e32 v144, 0xbfb8aa3b, v128
	v_mul_f32_e32 v145, 0xbfb8aa3b, v129
	v_exp_f32_e32 v144, v144
	v_exp_f32_e32 v145, v145
	v_mul_f32_e32 v146, 0xbfb8aa3b, v130
	v_mul_f32_e32 v147, 0xbfb8aa3b, v131
	v_exp_f32_e32 v146, v146
	v_exp_f32_e32 v147, v147
	v_add_f32_e32 v144, 1.0, v144
	v_add_f32_e32 v145, 1.0, v145
	v_rcp_f32_e32 v144, v144
	v_rcp_f32_e32 v145, v145
	v_add_f32_e32 v146, 1.0, v146
	v_add_f32_e32 v147, 1.0, v147
	v_rcp_f32_e32 v146, v146
	v_rcp_f32_e32 v147, v147
	v_pk_mul_f32 v[164:165], v[128:129], v[144:145]
	v_mul_f32_e32 v144, 0xbfb8aa3b, v120
	v_mul_f32_e32 v145, 0xbfb8aa3b, v121
	v_exp_f32_e32 v144, v144
	v_exp_f32_e32 v145, v145
	v_pk_mul_f32 v[166:167], v[130:131], v[146:147]
	v_mul_f32_e32 v146, 0xbfb8aa3b, v122
	v_mul_f32_e32 v147, 0xbfb8aa3b, v123
	v_exp_f32_e32 v146, v146
	v_exp_f32_e32 v147, v147
	v_add_f32_e32 v144, 1.0, v144
	v_add_f32_e32 v145, 1.0, v145
	v_rcp_f32_e32 v144, v144
	v_rcp_f32_e32 v145, v145
	v_or_b32_e32 v162, s11, v233
	v_add_f32_e32 v146, 1.0, v146
	v_add_f32_e32 v147, 1.0, v147
	v_rcp_f32_e32 v146, v146
	v_rcp_f32_e32 v147, v147
	v_ashrrev_i32_e32 v163, 31, v162
	v_pk_mul_f32 v[170:171], v[120:121], v[144:145]
	v_lshlrev_b64 v[144:145], 11, v[162:163]
	v_lshl_add_u64 v[144:145], s[50:51], 0, v[144:145]
	v_lshlrev_b64 v[160:161], 1, v[210:211]
	v_lshl_add_u64 v[144:145], v[144:145], 0, v[160:161]
	v_pk_mul_f32 v[168:169], v[122:123], v[146:147]
	s_waitcnt vmcnt(4)
	v_mov_b32_e32 v144, v188
	v_mov_b32_e32 v145, v189
	v_mov_b32_e32 v146, v190
	v_mov_b32_e32 v147, v191
	v_add_u32_e32 v187, 0x8000, v187
	global_load_dwordx4 v[188:191], v187, s[50:51]
	v_mov_b32_e32 v173, v211
	v_mov_b32_e32 v174, v211
	v_mov_b32_e32 v175, v211
	v_mov_b32_e32 v176, v211
	v_mov_b32_e32 v177, v211
	v_mov_b32_e32 v178, v211
	v_mov_b32_e32 v179, v211
	v_pk_mul_f32 v[170:171], v[124:125], v[170:171]
	v_pk_mul_f32 v[168:169], v[126:127], v[168:169]
	v_mov_b32_e32 v184, v211
	v_mov_b32_e32 v185, v211
	s_movk_i32 s16, 0x7ff
	v_cndmask_b32_e64 v172, v144, v156, s[4:5]
	v_cndmask_b32_e64 v156, v156, v144, s[0:1]
	s_nop 0
	v_mov_b32_dpp v173, v172 row_ror:1 row_mask:0xf bank_mask:0xf
	v_mov_b32_e32 v172, v211
	s_nop 1
	v_mov_b32_dpp v172, v156 row_ror:2 row_mask:0xf bank_mask:0xf
	v_cndmask_b32_e64 v156, v145, v157, s[4:5]
	v_cndmask_b32_e64 v157, v157, v145, s[0:1]
	v_lshlrev_b32_e32 v180, 16, v172
	v_mov_b32_dpp v174, v156 row_ror:1 row_mask:0xf bank_mask:0xf
	v_mov_b32_dpp v175, v157 row_ror:2 row_mask:0xf bank_mask:0xf
	v_cndmask_b32_e64 v156, v146, v158, s[4:5]
	v_cndmask_b32_e64 v157, v158, v146, s[0:1]
	v_lshlrev_b32_e32 v158, 16, v144
	v_mov_b32_dpp v176, v156 row_ror:1 row_mask:0xf bank_mask:0xf
	v_mov_b32_dpp v177, v157 row_ror:2 row_mask:0xf bank_mask:0xf
	v_cndmask_b32_e64 v156, v147, v159, s[4:5]
	v_cndmask_b32_e64 v157, v159, v147, s[0:1]
	v_lshlrev_b32_e32 v159, 16, v173
	v_mov_b32_dpp v178, v156 row_ror:1 row_mask:0xf bank_mask:0xf
	v_mov_b32_dpp v179, v157 row_ror:2 row_mask:0xf bank_mask:0xf
	v_mov_b32_e32 v156, v152
	v_mov_b32_e32 v157, v140
	v_pk_mul_f32 v[158:159], v[156:157], v[158:159]
	v_and_b32_e32 v172, 0xffff0000, v172
	v_fma_f32 v140, v136, v180, v159
	v_add_f32_e32 v180, v158, v140
	v_and_b32_e32 v159, 0xffff0000, v173
	v_and_b32_e32 v158, 0xffff0000, v144
	v_mov_b32_e32 v140, v153
	v_pk_mul_f32 v[152:153], v[140:141], v[158:159]
	v_lshlrev_b32_e32 v158, 16, v145
	v_fma_f32 v153, v137, v172, v153
	v_add_f32_e32 v172, v152, v153
	v_lshlrev_b32_e32 v159, 16, v174
	v_mov_b32_e32 v152, v154
	v_mov_b32_e32 v153, v142
	v_lshlrev_b32_e32 v173, 16, v175
	v_pk_mul_f32 v[158:159], v[152:153], v[158:159]
	v_and_b32_e32 v175, 0xffff0000, v175
	v_fma_f32 v142, v138, v173, v159
	v_add_f32_e32 v173, v158, v142
	v_and_b32_e32 v159, 0xffff0000, v174
	v_and_b32_e32 v158, 0xffff0000, v145
	v_mov_b32_e32 v142, v155
	v_pk_mul_f32 v[154:155], v[142:143], v[158:159]
	v_lshlrev_b32_e32 v158, 16, v146
	v_fma_f32 v155, v139, v175, v155
	v_add_f32_e32 v174, v154, v155
	v_lshlrev_b32_e32 v159, 16, v176
	v_mov_b32_e32 v154, v148
	v_mov_b32_e32 v155, v116
	v_lshlrev_b32_e32 v175, 16, v177
	v_pk_mul_f32 v[158:159], v[154:155], v[158:159]
	v_and_b32_e32 v177, 0xffff0000, v177
	v_fma_f32 v116, v112, v175, v159
	v_add_f32_e32 v175, v158, v116
	v_and_b32_e32 v159, 0xffff0000, v176
	v_and_b32_e32 v158, 0xffff0000, v146
	v_mov_b32_e32 v116, v149
	v_pk_mul_f32 v[148:149], v[116:117], v[158:159]
	v_mov_b32_e32 v158, v150
	v_fma_f32 v149, v113, v177, v149
	v_add_f32_e32 v176, v148, v149
	v_lshlrev_b32_e32 v148, 16, v147
	v_lshlrev_b32_e32 v149, 16, v178
	v_mov_b32_e32 v159, v118
	v_lshlrev_b32_e32 v177, 16, v179
	v_pk_mul_f32 v[148:149], v[158:159], v[148:149]
	v_and_b32_e32 v150, 0xffff0000, v179
	v_fma_f32 v118, v114, v177, v149
	v_add_f32_e32 v177, v148, v118
	v_and_b32_e32 v149, 0xffff0000, v178
	v_and_b32_e32 v148, 0xffff0000, v147
	v_mov_b32_e32 v118, v151
	v_pk_mul_f32 v[148:149], v[118:119], v[148:149]
	v_mov_b32_e32 v179, v211
	v_fma_f32 v149, v115, v150, v149
	v_add_f32_e32 v178, v148, v149
	v_pk_mul_f32 v[148:149], v[132:133], v[164:165]
	v_pk_mul_f32 v[150:151], v[134:135], v[166:167]
	v_mul_f32_e32 v148, v148, v180
	v_mul_f32_e32 v149, v149, v172
	v_cvt_pk_bf16_f32 v148, v148, v149
	v_mul_f32_e32 v149, v150, v173
	v_mul_f32_e32 v150, v151, v174
	v_cvt_pk_bf16_f32 v149, v149, v150
	v_mul_f32_e32 v150, v170, v175
	v_mul_f32_e32 v151, v171, v176
	v_cvt_pk_bf16_f32 v150, v150, v151
	v_mul_f32_e32 v151, v168, v177
	v_mul_f32_e32 v164, v169, v178
	v_cvt_pk_bf16_f32 v151, v151, v164
	v_lshlrev_b64 v[164:165], 12, v[162:163]
	v_lshl_add_u64 v[164:165], s[12:13], 0, v[164:165]
	v_lshl_add_u64 v[164:165], v[164:165], 0, v[160:161]
	s_cmp_lg_u32 s32, 0
	s_cbranch_scc1 .Lls_mb0_w
	global_store_dwordx4 v[164:165], v[148:151], off offset:2048
	s_branch .Lls_mb0_j
.Lls_mb0_w:
	global_store_dwordx4 v[164:165], v[148:151], off offset:2048 sc1
.Lls_mb0_j:
	v_or_b32_e32 v172, 16, v162
	v_ashrrev_i32_e32 v173, 31, v172
	v_mul_f32_e32 v148, 0xbfb8aa3b, v104
	v_mul_f32_e32 v149, 0xbfb8aa3b, v105
	v_exp_f32_e32 v148, v148
	v_exp_f32_e32 v149, v149
	v_mul_f32_e32 v150, 0xbfb8aa3b, v106
	v_mul_f32_e32 v151, 0xbfb8aa3b, v107
	v_exp_f32_e32 v150, v150
	v_exp_f32_e32 v151, v151
	v_add_f32_e32 v148, 1.0, v148
	v_add_f32_e32 v149, 1.0, v149
	v_rcp_f32_e32 v148, v148
	v_rcp_f32_e32 v149, v149
	v_add_f32_e32 v150, 1.0, v150
	v_add_f32_e32 v151, 1.0, v151
	v_rcp_f32_e32 v150, v150
	v_rcp_f32_e32 v151, v151
	v_pk_mul_f32 v[164:165], v[104:105], v[148:149]
	v_mul_f32_e32 v148, 0xbfb8aa3b, v96
	v_mul_f32_e32 v149, 0xbfb8aa3b, v97
	v_exp_f32_e32 v148, v148
	v_exp_f32_e32 v149, v149
	v_pk_mul_f32 v[166:167], v[106:107], v[150:151]
	v_mul_f32_e32 v150, 0xbfb8aa3b, v98
	v_mul_f32_e32 v151, 0xbfb8aa3b, v99
	v_exp_f32_e32 v150, v150
	v_exp_f32_e32 v151, v151
	v_add_f32_e32 v148, 1.0, v148
	v_add_f32_e32 v149, 1.0, v149
	v_rcp_f32_e32 v148, v148
	v_rcp_f32_e32 v149, v149
	v_add_f32_e32 v150, 1.0, v150
	v_add_f32_e32 v151, 1.0, v151
	v_rcp_f32_e32 v150, v150
	v_rcp_f32_e32 v151, v151
	v_pk_mul_f32 v[168:169], v[96:97], v[148:149]
	v_lshlrev_b64 v[148:149], 11, v[172:173]
	v_lshl_add_u64 v[148:149], s[50:51], 0, v[148:149]
	v_lshl_add_u64 v[148:149], v[148:149], 0, v[160:161]
	v_pk_mul_f32 v[170:171], v[98:99], v[150:151]
	s_waitcnt vmcnt(5)
	v_mov_b32_e32 v148, v192
	v_mov_b32_e32 v149, v193
	v_mov_b32_e32 v150, v194
	v_mov_b32_e32 v151, v195
	v_add_u32_e32 v187, 0x8000, v187
	global_load_dwordx4 v[192:195], v187, s[50:51]
	v_mov_b32_e32 v174, v211
	v_mov_b32_e32 v175, v211
	v_mov_b32_e32 v176, v211
	v_mov_b32_e32 v177, v211
	v_mov_b32_e32 v178, v211
	v_mov_b32_e32 v180, v211
	v_pk_mul_f32 v[166:167], v[110:111], v[166:167]
	v_pk_mul_f32 v[170:171], v[102:103], v[170:171]
	v_cndmask_b32_e64 v163, v148, v144, s[4:5]
	v_cndmask_b32_e64 v144, v144, v148, s[0:1]
	s_nop 0
	v_mov_b32_dpp v174, v163 row_ror:1 row_mask:0xf bank_mask:0xf
	v_mov_b32_e32 v163, v211
	s_nop 1
	v_mov_b32_dpp v163, v144 row_ror:2 row_mask:0xf bank_mask:0xf
	v_cndmask_b32_e64 v144, v149, v145, s[4:5]
	v_cndmask_b32_e64 v145, v145, v149, s[0:1]
	s_nop 0
	v_mov_b32_dpp v175, v144 row_ror:1 row_mask:0xf bank_mask:0xf
	v_mov_b32_dpp v176, v145 row_ror:2 row_mask:0xf bank_mask:0xf
	v_cndmask_b32_e64 v144, v150, v146, s[4:5]
	v_cndmask_b32_e64 v145, v146, v150, s[0:1]
	s_nop 0
	v_mov_b32_dpp v177, v144 row_ror:1 row_mask:0xf bank_mask:0xf
	v_mov_b32_dpp v178, v145 row_ror:2 row_mask:0xf bank_mask:0xf
	v_cndmask_b32_e64 v144, v151, v147, s[4:5]
	v_cndmask_b32_e64 v145, v147, v151, s[0:1]
	v_pk_mul_f32 v[146:147], v[100:101], v[168:169]
	v_mov_b32_dpp v179, v144 row_ror:1 row_mask:0xf bank_mask:0xf
	v_mov_b32_dpp v180, v145 row_ror:2 row_mask:0xf bank_mask:0xf
	v_lshlrev_b32_e32 v145, 16, v174
	v_lshlrev_b32_e32 v144, 16, v148
	v_lshlrev_b32_e32 v168, 16, v163
	v_pk_mul_f32 v[144:145], v[156:157], v[144:145]
	v_and_b32_e32 v163, 0xffff0000, v163
	v_fma_f32 v145, v136, v168, v145
	v_add_f32_e32 v168, v144, v145
	v_and_b32_e32 v145, 0xffff0000, v174
	v_and_b32_e32 v144, 0xffff0000, v148
	v_pk_mul_f32 v[144:145], v[140:141], v[144:145]
	v_lshlrev_b32_e32 v169, 16, v176
	v_fma_f32 v145, v137, v163, v145
	v_add_f32_e32 v163, v144, v145
	v_lshlrev_b32_e32 v145, 16, v175
	v_lshlrev_b32_e32 v144, 16, v149
	v_pk_mul_f32 v[144:145], v[152:153], v[144:145]
	v_and_b32_e32 v174, 0xffff0000, v176
	v_fma_f32 v145, v138, v169, v145
	v_add_f32_e32 v169, v144, v145
	v_and_b32_e32 v145, 0xffff0000, v175
	v_and_b32_e32 v144, 0xffff0000, v149
	v_pk_mul_f32 v[144:145], v[142:143], v[144:145]
	v_lshlrev_b32_e32 v175, 16, v178
	v_fma_f32 v145, v139, v174, v145
	v_add_f32_e32 v174, v144, v145
	v_lshlrev_b32_e32 v145, 16, v177
	v_lshlrev_b32_e32 v144, 16, v150
	v_pk_mul_f32 v[144:145], v[154:155], v[144:145]
	v_and_b32_e32 v176, 0xffff0000, v178
	v_fma_f32 v145, v112, v175, v145
	v_add_f32_e32 v175, v144, v145
	v_and_b32_e32 v145, 0xffff0000, v177
	v_and_b32_e32 v144, 0xffff0000, v150
	v_pk_mul_f32 v[144:145], v[116:117], v[144:145]
	v_lshlrev_b32_e32 v177, 16, v180
	v_fma_f32 v145, v113, v176, v145
	v_add_f32_e32 v176, v144, v145
	v_lshlrev_b32_e32 v145, 16, v179
	v_lshlrev_b32_e32 v144, 16, v151
	v_pk_mul_f32 v[144:145], v[158:159], v[144:145]
	v_and_b32_e32 v178, 0xffff0000, v180
	v_fma_f32 v145, v114, v177, v145
	v_add_f32_e32 v177, v144, v145
	v_and_b32_e32 v145, 0xffff0000, v179
	v_and_b32_e32 v144, 0xffff0000, v151
	v_pk_mul_f32 v[144:145], v[118:119], v[144:145]
	v_mul_f32_e32 v146, v146, v175
	v_fma_f32 v145, v115, v178, v145
	v_add_f32_e32 v178, v144, v145
	v_pk_mul_f32 v[144:145], v[108:109], v[164:165]
	v_lshlrev_b64 v[164:165], 12, v[172:173]
	v_mul_f32_e32 v144, v144, v168
	v_mul_f32_e32 v145, v145, v163
	v_cvt_pk_bf16_f32 v144, v144, v145
	v_mul_f32_e32 v145, v166, v169
	v_mul_f32_e32 v147, v147, v176
	v_lshl_add_u64 v[164:165], s[12:13], 0, v[164:165]
	v_mul_f32_e32 v163, v167, v174
	v_cvt_pk_bf16_f32 v145, v145, v163
	v_cvt_pk_bf16_f32 v146, v146, v147
	v_mul_f32_e32 v147, v170, v177
	v_lshl_add_u64 v[164:165], v[164:165], 0, v[160:161]
	v_mul_f32_e32 v163, v171, v178
	v_cvt_pk_bf16_f32 v147, v147, v163
	s_cmp_lg_u32 s32, 0
	s_cbranch_scc1 .Lls_mb1_w
	global_store_dwordx4 v[164:165], v[144:147], off offset:2048
	s_branch .Lls_mb1_j
.Lls_mb1_w:
	global_store_dwordx4 v[164:165], v[144:147], off offset:2048 sc1
.Lls_mb1_j:
	v_or_b32_e32 v172, 32, v162
	v_ashrrev_i32_e32 v173, 31, v172
	v_mul_f32_e32 v144, 0xbfb8aa3b, v88
	v_mul_f32_e32 v145, 0xbfb8aa3b, v89
	v_exp_f32_e32 v144, v144
	v_exp_f32_e32 v145, v145
	v_mul_f32_e32 v146, 0xbfb8aa3b, v90
	v_mul_f32_e32 v147, 0xbfb8aa3b, v91
	v_exp_f32_e32 v146, v146
	v_exp_f32_e32 v147, v147
	v_add_f32_e32 v144, 1.0, v144
	v_add_f32_e32 v145, 1.0, v145
	v_rcp_f32_e32 v144, v144
	v_rcp_f32_e32 v145, v145
	v_add_f32_e32 v146, 1.0, v146
	v_add_f32_e32 v147, 1.0, v147
	v_rcp_f32_e32 v146, v146
	v_rcp_f32_e32 v147, v147
	v_pk_mul_f32 v[164:165], v[88:89], v[144:145]
	v_mul_f32_e32 v144, 0xbfb8aa3b, v80
	v_mul_f32_e32 v145, 0xbfb8aa3b, v81
	v_exp_f32_e32 v144, v144
	v_exp_f32_e32 v145, v145
	v_pk_mul_f32 v[166:167], v[90:91], v[146:147]
	v_mul_f32_e32 v146, 0xbfb8aa3b, v82
	v_mul_f32_e32 v147, 0xbfb8aa3b, v83
	v_exp_f32_e32 v146, v146
	v_exp_f32_e32 v147, v147
	v_add_f32_e32 v144, 1.0, v144
	v_add_f32_e32 v145, 1.0, v145
	v_rcp_f32_e32 v144, v144
	v_rcp_f32_e32 v145, v145
	v_add_f32_e32 v146, 1.0, v146
	v_add_f32_e32 v147, 1.0, v147
	v_rcp_f32_e32 v146, v146
	v_rcp_f32_e32 v147, v147
	v_pk_mul_f32 v[168:169], v[80:81], v[144:145]
	v_lshlrev_b64 v[144:145], 11, v[172:173]
	v_lshl_add_u64 v[144:145], s[50:51], 0, v[144:145]
	v_lshl_add_u64 v[144:145], v[144:145], 0, v[160:161]
	v_pk_mul_f32 v[170:171], v[82:83], v[146:147]
	s_waitcnt vmcnt(6)
	v_mov_b32_e32 v144, v196
	v_mov_b32_e32 v145, v197
	v_mov_b32_e32 v146, v198
	v_mov_b32_e32 v147, v199
	v_add_u32_e32 v187, 0x8000, v187
	global_load_dwordx4 v[196:199], v187, s[50:51]
	v_mov_b32_e32 v174, v211
	v_mov_b32_e32 v175, v211
	v_mov_b32_e32 v176, v211
	v_mov_b32_e32 v177, v211
	v_mov_b32_e32 v178, v211
	v_mov_b32_e32 v179, v211
	v_mov_b32_e32 v180, v211
	v_pk_mul_f32 v[166:167], v[94:95], v[166:167]
	v_pk_mul_f32 v[170:171], v[86:87], v[170:171]
	v_cndmask_b32_e64 v163, v144, v148, s[4:5]
	v_cndmask_b32_e64 v148, v148, v144, s[0:1]
	s_nop 0
	v_mov_b32_dpp v174, v163 row_ror:1 row_mask:0xf bank_mask:0xf
	v_mov_b32_e32 v163, v211
	s_nop 1
	v_mov_b32_dpp v163, v148 row_ror:2 row_mask:0xf bank_mask:0xf
	v_cndmask_b32_e64 v148, v145, v149, s[4:5]
	v_cndmask_b32_e64 v149, v149, v145, s[0:1]
	s_nop 0
	v_mov_b32_dpp v175, v148 row_ror:1 row_mask:0xf bank_mask:0xf
	v_mov_b32_dpp v176, v149 row_ror:2 row_mask:0xf bank_mask:0xf
	v_cndmask_b32_e64 v148, v146, v150, s[4:5]
	v_cndmask_b32_e64 v149, v150, v146, s[0:1]
	s_nop 0
	v_mov_b32_dpp v177, v148 row_ror:1 row_mask:0xf bank_mask:0xf
	v_mov_b32_dpp v178, v149 row_ror:2 row_mask:0xf bank_mask:0xf
	v_cndmask_b32_e64 v148, v147, v151, s[4:5]
	v_cndmask_b32_e64 v149, v151, v147, s[0:1]
	v_pk_mul_f32 v[150:151], v[84:85], v[168:169]
	v_mov_b32_dpp v179, v148 row_ror:1 row_mask:0xf bank_mask:0xf
	v_mov_b32_dpp v180, v149 row_ror:2 row_mask:0xf bank_mask:0xf
	v_lshlrev_b32_e32 v149, 16, v174
	v_lshlrev_b32_e32 v148, 16, v144
	v_lshlrev_b32_e32 v168, 16, v163
	v_pk_mul_f32 v[148:149], v[156:157], v[148:149]
	v_and_b32_e32 v163, 0xffff0000, v163
	v_fma_f32 v149, v136, v168, v149
	v_add_f32_e32 v168, v148, v149
	v_and_b32_e32 v149, 0xffff0000, v174
	v_and_b32_e32 v148, 0xffff0000, v144
	v_pk_mul_f32 v[148:149], v[140:141], v[148:149]
	v_lshlrev_b32_e32 v169, 16, v176
	v_fma_f32 v149, v137, v163, v149
	v_add_f32_e32 v163, v148, v149
	v_lshlrev_b32_e32 v149, 16, v175
	v_lshlrev_b32_e32 v148, 16, v145
	v_pk_mul_f32 v[148:149], v[152:153], v[148:149]
	v_and_b32_e32 v174, 0xffff0000, v176
	v_fma_f32 v149, v138, v169, v149
	v_add_f32_e32 v169, v148, v149
	v_and_b32_e32 v149, 0xffff0000, v175
	v_and_b32_e32 v148, 0xffff0000, v145
	v_pk_mul_f32 v[148:149], v[142:143], v[148:149]
	v_lshlrev_b32_e32 v175, 16, v178
	v_fma_f32 v149, v139, v174, v149
	v_add_f32_e32 v174, v148, v149
	v_lshlrev_b32_e32 v149, 16, v177
	v_lshlrev_b32_e32 v148, 16, v146
	v_pk_mul_f32 v[148:149], v[154:155], v[148:149]
	v_and_b32_e32 v176, 0xffff0000, v178
	v_fma_f32 v149, v112, v175, v149
	v_add_f32_e32 v175, v148, v149
	v_and_b32_e32 v149, 0xffff0000, v177
	v_and_b32_e32 v148, 0xffff0000, v146
	v_pk_mul_f32 v[148:149], v[116:117], v[148:149]
	v_lshlrev_b32_e32 v177, 16, v180
	v_fma_f32 v149, v113, v176, v149
	v_add_f32_e32 v176, v148, v149
	v_lshlrev_b32_e32 v149, 16, v179
	v_lshlrev_b32_e32 v148, 16, v147
	v_pk_mul_f32 v[148:149], v[158:159], v[148:149]
	v_and_b32_e32 v178, 0xffff0000, v180
	v_fma_f32 v149, v114, v177, v149
	v_add_f32_e32 v177, v148, v149
	v_and_b32_e32 v149, 0xffff0000, v179
	v_and_b32_e32 v148, 0xffff0000, v147
	v_pk_mul_f32 v[148:149], v[118:119], v[148:149]
	v_mul_f32_e32 v150, v150, v175
	v_fma_f32 v149, v115, v178, v149
	v_add_f32_e32 v178, v148, v149
	v_pk_mul_f32 v[148:149], v[92:93], v[164:165]
	v_mul_f32_e32 v151, v151, v176
	v_mul_f32_e32 v148, v148, v168
	v_mul_f32_e32 v149, v149, v163
	v_or_b32_e32 v168, 48, v162
	v_cvt_pk_bf16_f32 v148, v148, v149
	v_mul_f32_e32 v149, v166, v169
	v_mul_f32_e32 v163, v167, v174
	v_lshlrev_b64 v[164:165], 12, v[172:173]
	v_ashrrev_i32_e32 v169, 31, v168
	v_cvt_pk_bf16_f32 v149, v149, v163
	v_cvt_pk_bf16_f32 v150, v150, v151
	v_mul_f32_e32 v151, v170, v177
	v_mul_f32_e32 v163, v171, v178
	v_lshl_add_u64 v[164:165], s[12:13], 0, v[164:165]
	v_lshlrev_b64 v[170:171], 11, v[168:169]
	v_lshl_add_u64 v[164:165], v[164:165], 0, v[160:161]
	v_lshl_add_u64 v[170:171], s[50:51], 0, v[170:171]
	v_cvt_pk_bf16_f32 v151, v151, v163
	s_cmp_lg_u32 s32, 0
	s_cbranch_scc1 .Lls_mb2_w
	global_store_dwordx4 v[164:165], v[148:151], off offset:2048
	s_branch .Lls_mb2_j

.Lls_mb2_j:
	v_lshl_add_u64 v[170:171], v[170:171], 0, v[160:161]
	s_waitcnt vmcnt(7)
	v_mov_b32_e32 v176, v228
	v_mov_b32_e32 v177, v229
	v_mov_b32_e32 v178, v230
	v_mov_b32_e32 v179, v231
	v_mul_f32_e32 v148, 0xbfb8aa3b, v72
	v_mul_f32_e32 v149, 0xbfb8aa3b, v73
	v_exp_f32_e32 v148, v148
	v_exp_f32_e32 v149, v149
	v_mul_f32_e32 v150, 0xbfb8aa3b, v74
	v_mul_f32_e32 v151, 0xbfb8aa3b, v75
	v_add_f32_e32 v148, 1.0, v148
	v_add_f32_e32 v149, 1.0, v149
	v_rcp_f32_e32 v148, v148
	v_rcp_f32_e32 v149, v149
	v_exp_f32_e32 v150, v150
	v_exp_f32_e32 v151, v151
	v_mov_b32_e32 v170, v211
	v_pk_mul_f32 v[164:165], v[72:73], v[148:149]
	v_mul_f32_e32 v148, 0xbfb8aa3b, v64
	v_mul_f32_e32 v149, 0xbfb8aa3b, v65
	v_exp_f32_e32 v148, v148
	v_exp_f32_e32 v149, v149
	v_add_f32_e32 v150, 1.0, v150
	v_add_f32_e32 v151, 1.0, v151
	v_add_f32_e32 v148, 1.0, v148
	v_add_f32_e32 v149, 1.0, v149
	v_rcp_f32_e32 v148, v148
	v_rcp_f32_e32 v149, v149
	v_rcp_f32_e32 v150, v150
	v_rcp_f32_e32 v151, v151
	v_mov_b32_e32 v172, v211
	v_mov_b32_e32 v173, v211
	v_mov_b32_e32 v174, v211
	v_mov_b32_e32 v175, v211
	v_pk_mul_f32 v[148:149], v[64:65], v[148:149]
	v_pk_mul_f32 v[166:167], v[74:75], v[150:151]
	v_mul_f32_e32 v150, 0xbfb8aa3b, v66
	v_mul_f32_e32 v151, 0xbfb8aa3b, v67
	v_pk_mul_f32 v[182:183], v[68:69], v[148:149]
	v_exp_f32_e32 v150, v150
	v_exp_f32_e32 v151, v151
	v_pk_mul_f32 v[164:165], v[76:77], v[164:165]
	v_pk_mul_f32 v[166:167], v[78:79], v[166:167]
	v_add_f32_e32 v150, 1.0, v150
	v_add_f32_e32 v151, 1.0, v151
	v_rcp_f32_e32 v150, v150
	v_rcp_f32_e32 v151, v151
	v_cndmask_b32_e64 v163, v176, v144, s[4:5]
	v_cndmask_b32_e64 v144, v144, v176, s[0:1]
	s_nop 0
	v_mov_b32_dpp v170, v163 row_ror:1 row_mask:0xf bank_mask:0xf
	v_mov_b32_e32 v163, v211
	v_and_b32_e32 v171, 0xffff0000, v170
	v_pk_mul_f32 v[150:151], v[66:67], v[150:151]
	v_mov_b32_dpp v163, v144 row_ror:2 row_mask:0xf bank_mask:0xf
	v_cndmask_b32_e64 v144, v177, v145, s[4:5]
	v_cndmask_b32_e64 v145, v145, v177, s[0:1]
	v_lshlrev_b32_e32 v148, 16, v163
	v_mov_b32_dpp v172, v144 row_ror:1 row_mask:0xf bank_mask:0xf
	v_mov_b32_dpp v173, v145 row_ror:2 row_mask:0xf bank_mask:0xf
	v_cndmask_b32_e64 v144, v178, v146, s[4:5]
	v_cndmask_b32_e64 v145, v146, v178, s[0:1]
	v_pk_mul_f32 v[180:181], v[70:71], v[150:151]
	v_mov_b32_dpp v174, v144 row_ror:1 row_mask:0xf bank_mask:0xf
	v_mov_b32_dpp v175, v145 row_ror:2 row_mask:0xf bank_mask:0xf
	v_cndmask_b32_e64 v144, v179, v147, s[4:5]
	v_cndmask_b32_e64 v145, v147, v179, s[0:1]
	s_nop 0
	v_mov_b32_dpp v184, v144 row_ror:1 row_mask:0xf bank_mask:0xf
	v_mov_b32_dpp v185, v145 row_ror:2 row_mask:0xf bank_mask:0xf
	v_lshlrev_b32_e32 v145, 16, v170
	v_lshlrev_b32_e32 v144, 16, v176
	v_pk_mul_f32 v[146:147], v[156:157], v[144:145]
	v_and_b32_e32 v170, 0xffff0000, v176
	v_fma_f32 v145, v136, v148, v147
	v_add_f32_e32 v186, v146, v145
	v_and_b32_e32 v145, 0xffff0000, v163
	v_pk_mul_f32 v[146:147], v[140:141], v[170:171]
	s_nop 0
	v_fma_f32 v145, v137, v145, v147
	v_add_f32_e32 v163, v146, v145
	v_lshlrev_b32_e32 v147, 16, v172
	v_lshlrev_b32_e32 v146, 16, v177
	v_lshlrev_b32_e32 v145, 16, v173
	v_pk_mul_f32 v[148:149], v[152:153], v[146:147]
	v_mul_f32_e32 v163, v165, v163
	v_fma_f32 v145, v138, v145, v149
	v_add_f32_e32 v147, v148, v145
	v_and_b32_e32 v145, 0xffff0000, v173
	v_and_b32_e32 v173, 0xffff0000, v172
	v_and_b32_e32 v172, 0xffff0000, v177
	v_pk_mul_f32 v[148:149], v[142:143], v[172:173]
	v_mul_f32_e32 v147, v166, v147
	v_fma_f32 v145, v139, v145, v149
	v_add_f32_e32 v171, v148, v145
	v_lshlrev_b32_e32 v149, 16, v174
	v_lshlrev_b32_e32 v148, 16, v178
	v_lshlrev_b32_e32 v145, 16, v175
	v_pk_mul_f32 v[150:151], v[154:155], v[148:149]
	s_nop 0
	v_fma_f32 v145, v112, v145, v151
	v_add_f32_e32 v149, v150, v145
	v_and_b32_e32 v145, 0xffff0000, v175
	v_and_b32_e32 v175, 0xffff0000, v174
	v_and_b32_e32 v174, 0xffff0000, v178
	v_pk_mul_f32 v[150:151], v[116:117], v[174:175]
	s_nop 0
	v_fma_f32 v145, v113, v145, v151
	v_add_f32_e32 v173, v150, v145
	v_lshlrev_b32_e32 v151, 16, v184
	v_lshlrev_b32_e32 v150, 16, v179
	v_lshlrev_b32_e32 v145, 16, v185
	v_pk_mul_f32 v[176:177], v[158:159], v[150:151]
	s_nop 0
	v_fma_f32 v145, v114, v145, v177
	v_add_f32_e32 v151, v176, v145
	v_and_b32_e32 v177, 0xffff0000, v184
	v_and_b32_e32 v176, 0xffff0000, v179
	v_and_b32_e32 v145, 0xffff0000, v185
	v_pk_mul_f32 v[178:179], v[118:119], v[176:177]
	s_nop 0
	v_fma_f32 v145, v115, v145, v179
	v_add_f32_e32 v175, v178, v145
	v_bitop3_b32 v145, v162, s16, 48 bitop3:0xc8
	v_mul_f32_e32 v162, v164, v186
	v_cvt_pk_bf16_f32 v162, v162, v163
	v_mul_f32_e32 v163, v167, v171
	v_lshlrev_b64 v[166:167], 12, v[168:169]
	v_lshl_add_u64 v[166:167], s[12:13], 0, v[166:167]
	s_movk_i32 s16, 0x7fd
	v_cvt_pk_bf16_f32 v163, v147, v163
	v_mul_f32_e32 v147, v182, v149
	v_mul_f32_e32 v149, v183, v173
	v_lshl_add_u64 v[166:167], v[166:167], 0, v[160:161]
	v_cmp_lt_u32_e32 vcc, s16, v145
	v_cvt_pk_bf16_f32 v164, v147, v149
	v_mul_f32_e32 v147, v180, v151
	v_mul_f32_e32 v149, v181, v175
	v_cvt_pk_bf16_f32 v165, v147, v149
	s_cmp_lg_u32 s32, 0
	s_cbranch_scc1 .Lls_mb3_w
	global_store_dwordx4 v[166:167], v[162:165], off offset:2048
	s_branch .Lls_mb3_j
.Lls_mb3_w:
	global_store_dwordx4 v[166:167], v[162:165], off offset:2048 sc1
.Lls_mb3_j:
	s_and_saveexec_b64 s[40:41], vcc
	s_cbranch_execz .LBB0_316
	v_lshrrev_b32_e32 v147, 21, v169
	v_add_u32_e32 v147, v168, v147
	v_ashrrev_i32_e32 v162, 11, v147
	v_ashrrev_i32_e32 v163, 31, v162
	v_add_u32_e32 v164, 0xfffff802, v145
	v_mov_b32_e32 v165, v211
	v_lshlrev_b64 v[162:163], 13, v[162:163]
	v_lshl_add_u64 v[162:163], s[18:19], 0, v[162:163]
	v_lshlrev_b64 v[164:165], 12, v[164:165]
	v_lshl_add_u64 v[162:163], v[162:163], 0, v[164:165]
	v_lshl_add_u64 v[162:163], v[210:211], 2, v[162:163]
	v_mov_b32_e32 v145, v170
	v_mov_b32_e32 v147, v172
	v_mov_b32_e32 v149, v174
	v_mov_b32_e32 v151, v176
	global_store_dwordx4 v[162:163], v[144:147], off
	global_store_dwordx4 v[162:163], v[148:151], off offset:16
.LBB0_316:
	s_or_b64 exec, exec, s[40:41]
	s_addk_i32 s11, 0x80
	s_and_b32 s16, s11, 0x7c0
	s_cmp_lg_u32 s16, 0
	s_cselect_b64 s[16:17], -1, 0
	s_and_b64 s[16:17], s[8:9], s[16:17]
	v_mov_b32_e32 v148, 0
	v_mov_b32_e32 v149, 0
	v_mov_b32_e32 v150, 0
	v_mov_b32_e32 v151, 0
	v_mov_b32_e32 v148, v250
	v_mov_b32_e32 v149, v251
	v_mov_b32_e32 v150, v252
	v_mov_b32_e32 v151, v253
	v_mul_f32_e32 v144, 0xbfb8aa3b, v56
	v_mul_f32_e32 v145, 0xbfb8aa3b, v57
	v_exp_f32_e32 v144, v144
	v_exp_f32_e32 v145, v145
	v_mul_f32_e32 v146, 0xbfb8aa3b, v58
	v_mul_f32_e32 v147, 0xbfb8aa3b, v59
	v_exp_f32_e32 v146, v146
	v_exp_f32_e32 v147, v147
	v_add_f32_e32 v144, 1.0, v144
	v_add_f32_e32 v145, 1.0, v145
	v_rcp_f32_e32 v144, v144
	v_rcp_f32_e32 v145, v145
	v_add_f32_e32 v146, 1.0, v146
	v_add_f32_e32 v147, 1.0, v147
	v_rcp_f32_e32 v146, v146
	v_rcp_f32_e32 v147, v147
	v_pk_mul_f32 v[164:165], v[56:57], v[144:145]
	v_mul_f32_e32 v144, 0xbfb8aa3b, v48
	v_mul_f32_e32 v145, 0xbfb8aa3b, v49
	v_exp_f32_e32 v144, v144
	v_exp_f32_e32 v145, v145
	v_pk_mul_f32 v[166:167], v[58:59], v[146:147]
	v_mul_f32_e32 v146, 0xbfb8aa3b, v50
	v_mul_f32_e32 v147, 0xbfb8aa3b, v51
	v_exp_f32_e32 v146, v146
	v_exp_f32_e32 v147, v147
	v_add_f32_e32 v144, 1.0, v144
	v_add_f32_e32 v145, 1.0, v145
	v_rcp_f32_e32 v144, v144
	v_rcp_f32_e32 v145, v145
	v_or_b32_e32 v162, s11, v233
	v_add_f32_e32 v146, 1.0, v146
	v_add_f32_e32 v147, 1.0, v147
	v_rcp_f32_e32 v146, v146
	v_rcp_f32_e32 v147, v147
	v_ashrrev_i32_e32 v163, 31, v162
	v_pk_mul_f32 v[168:169], v[48:49], v[144:145]
	v_lshlrev_b64 v[144:145], 11, v[162:163]
	v_lshl_add_u64 v[144:145], s[50:51], 0, v[144:145]
	v_lshl_add_u64 v[144:145], v[144:145], 0, v[160:161]
	v_pk_mul_f32 v[170:171], v[50:51], v[146:147]
	s_waitcnt vmcnt(7)
	v_mov_b32_e32 v144, v246
	v_mov_b32_e32 v145, v247
	v_mov_b32_e32 v146, v248
	v_mov_b32_e32 v147, v249
	v_mov_b32_e32 v173, v211
	v_mov_b32_e32 v174, v211
	v_mov_b32_e32 v175, v211
	v_mov_b32_e32 v176, v211
	v_mov_b32_e32 v177, v211
	v_mov_b32_e32 v178, v211
	v_mov_b32_e32 v179, v211
	v_pk_mul_f32 v[166:167], v[62:63], v[166:167]
	v_pk_mul_f32 v[170:171], v[54:55], v[170:171]
	v_mov_b32_e32 v180, v211
	s_movk_i32 s8, 0x7ff
	v_cndmask_b32_e64 v172, v144, v148, s[4:5]
	v_cndmask_b32_e64 v148, v148, v144, s[0:1]
	s_nop 0
	v_mov_b32_dpp v173, v172 row_ror:1 row_mask:0xf bank_mask:0xf
	v_mov_b32_e32 v172, v211
	s_nop 1
	v_mov_b32_dpp v172, v148 row_ror:2 row_mask:0xf bank_mask:0xf
	v_cndmask_b32_e64 v148, v145, v149, s[4:5]
	v_cndmask_b32_e64 v149, v149, v145, s[0:1]
	s_nop 0
	v_mov_b32_dpp v174, v148 row_ror:1 row_mask:0xf bank_mask:0xf
	v_mov_b32_dpp v175, v149 row_ror:2 row_mask:0xf bank_mask:0xf
	v_cndmask_b32_e64 v148, v146, v150, s[4:5]
	v_cndmask_b32_e64 v149, v150, v146, s[0:1]
	s_nop 0
	v_mov_b32_dpp v176, v148 row_ror:1 row_mask:0xf bank_mask:0xf
	v_mov_b32_dpp v177, v149 row_ror:2 row_mask:0xf bank_mask:0xf
	v_cndmask_b32_e64 v148, v147, v151, s[4:5]
	v_cndmask_b32_e64 v149, v151, v147, s[0:1]
	v_pk_mul_f32 v[150:151], v[52:53], v[168:169]
	v_mov_b32_dpp v178, v148 row_ror:1 row_mask:0xf bank_mask:0xf
	v_mov_b32_dpp v179, v149 row_ror:2 row_mask:0xf bank_mask:0xf
	v_lshlrev_b32_e32 v148, 16, v144
	v_lshlrev_b32_e32 v149, 16, v173
	v_lshlrev_b32_e32 v168, 16, v172
	v_pk_mul_f32 v[148:149], v[156:157], v[148:149]
	v_and_b32_e32 v169, 0xffff0000, v172
	v_fma_f32 v149, v136, v168, v149
	v_add_f32_e32 v168, v148, v149
	v_and_b32_e32 v149, 0xffff0000, v173
	v_and_b32_e32 v148, 0xffff0000, v144
	v_pk_mul_f32 v[148:149], v[140:141], v[148:149]
	v_lshlrev_b32_e32 v172, 16, v175
	v_fma_f32 v149, v137, v169, v149
	v_add_f32_e32 v169, v148, v149
	v_lshlrev_b32_e32 v148, 16, v145
	v_lshlrev_b32_e32 v149, 16, v174
	v_pk_mul_f32 v[148:149], v[152:153], v[148:149]
	v_and_b32_e32 v173, 0xffff0000, v175
	v_fma_f32 v149, v138, v172, v149
	v_add_f32_e32 v172, v148, v149
	v_and_b32_e32 v149, 0xffff0000, v174
	v_and_b32_e32 v148, 0xffff0000, v145
	v_pk_mul_f32 v[148:149], v[142:143], v[148:149]
	v_lshlrev_b32_e32 v174, 16, v177
	v_fma_f32 v149, v139, v173, v149
	v_add_f32_e32 v173, v148, v149
	v_lshlrev_b32_e32 v148, 16, v146
	v_lshlrev_b32_e32 v149, 16, v176
	v_pk_mul_f32 v[148:149], v[154:155], v[148:149]
	v_and_b32_e32 v175, 0xffff0000, v177
	v_fma_f32 v149, v112, v174, v149
	v_add_f32_e32 v174, v148, v149
	v_and_b32_e32 v149, 0xffff0000, v176
	v_and_b32_e32 v148, 0xffff0000, v146
	v_pk_mul_f32 v[148:149], v[116:117], v[148:149]
	v_lshlrev_b32_e32 v176, 16, v179
	v_fma_f32 v149, v113, v175, v149
	v_add_f32_e32 v175, v148, v149
	v_lshlrev_b32_e32 v148, 16, v147
	v_lshlrev_b32_e32 v149, 16, v178
	v_pk_mul_f32 v[148:149], v[158:159], v[148:149]
	v_and_b32_e32 v177, 0xffff0000, v179
	v_fma_f32 v149, v114, v176, v149
	v_add_f32_e32 v176, v148, v149
	v_and_b32_e32 v149, 0xffff0000, v178
	v_and_b32_e32 v148, 0xffff0000, v147
	v_pk_mul_f32 v[148:149], v[118:119], v[148:149]
	v_mul_f32_e32 v150, v150, v174
	v_fma_f32 v149, v115, v177, v149
	v_add_f32_e32 v177, v148, v149
	v_pk_mul_f32 v[148:149], v[60:61], v[164:165]
	v_mul_f32_e32 v164, v167, v173
	v_mul_f32_e32 v148, v148, v168
	v_mul_f32_e32 v149, v149, v169
	v_cvt_pk_bf16_f32 v148, v148, v149
	v_mul_f32_e32 v149, v166, v172
	v_mul_f32_e32 v151, v151, v175
	v_cvt_pk_bf16_f32 v149, v149, v164
	v_cvt_pk_bf16_f32 v150, v150, v151
	v_mul_f32_e32 v151, v170, v176
	v_mul_f32_e32 v164, v171, v177
	v_cvt_pk_bf16_f32 v151, v151, v164
	v_lshlrev_b64 v[164:165], 12, v[162:163]
	v_lshl_add_u64 v[164:165], s[12:13], 0, v[164:165]
	v_lshl_add_u64 v[164:165], v[164:165], 0, v[160:161]
	s_cmp_lg_u32 s32, 0
	s_cbranch_scc1 .Lls_mb4_w
	global_store_dwordx4 v[164:165], v[148:151], off offset:2048
	s_branch .Lls_mb4_j

.Lls_mb4_j:
	v_or_b32_e32 v172, 16, v162
	v_ashrrev_i32_e32 v173, 31, v172
	v_mul_f32_e32 v148, 0xbfb8aa3b, v40
	v_mul_f32_e32 v149, 0xbfb8aa3b, v41
	v_exp_f32_e32 v148, v148
	v_exp_f32_e32 v149, v149
	v_mul_f32_e32 v150, 0xbfb8aa3b, v42
	v_mul_f32_e32 v151, 0xbfb8aa3b, v43
	v_exp_f32_e32 v150, v150
	v_exp_f32_e32 v151, v151
	v_add_f32_e32 v148, 1.0, v148
	v_add_f32_e32 v149, 1.0, v149
	v_rcp_f32_e32 v148, v148
	v_rcp_f32_e32 v149, v149
	v_add_f32_e32 v150, 1.0, v150
	v_add_f32_e32 v151, 1.0, v151
	v_rcp_f32_e32 v150, v150
	v_rcp_f32_e32 v151, v151
	v_pk_mul_f32 v[164:165], v[40:41], v[148:149]
	v_mul_f32_e32 v148, 0xbfb8aa3b, v32
	v_mul_f32_e32 v149, 0xbfb8aa3b, v33
	v_exp_f32_e32 v148, v148
	v_exp_f32_e32 v149, v149
	v_pk_mul_f32 v[166:167], v[42:43], v[150:151]
	v_mul_f32_e32 v150, 0xbfb8aa3b, v34
	v_mul_f32_e32 v151, 0xbfb8aa3b, v35
	v_exp_f32_e32 v150, v150
	v_exp_f32_e32 v151, v151
	v_add_f32_e32 v148, 1.0, v148
	v_add_f32_e32 v149, 1.0, v149
	v_rcp_f32_e32 v148, v148
	v_rcp_f32_e32 v149, v149
	v_add_f32_e32 v150, 1.0, v150
	v_add_f32_e32 v151, 1.0, v151
	v_rcp_f32_e32 v150, v150
	v_rcp_f32_e32 v151, v151
	v_pk_mul_f32 v[168:169], v[32:33], v[148:149]
	v_lshlrev_b64 v[148:149], 11, v[172:173]
	v_lshl_add_u64 v[148:149], s[50:51], 0, v[148:149]
	v_lshl_add_u64 v[148:149], v[148:149], 0, v[160:161]
	v_pk_mul_f32 v[170:171], v[34:35], v[150:151]
	s_waitcnt vmcnt(7)
	v_mov_b32_e32 v148, v188
	v_mov_b32_e32 v149, v189
	v_mov_b32_e32 v150, v190
	v_mov_b32_e32 v151, v191
	v_mov_b32_e32 v174, v211
	v_mov_b32_e32 v175, v211
	v_mov_b32_e32 v176, v211
	v_mov_b32_e32 v177, v211
	v_mov_b32_e32 v178, v211
	v_mov_b32_e32 v179, v211
	v_pk_mul_f32 v[166:167], v[46:47], v[166:167]
	v_pk_mul_f32 v[170:171], v[38:39], v[170:171]
	v_cndmask_b32_e64 v163, v148, v144, s[4:5]
	v_cndmask_b32_e64 v144, v144, v148, s[0:1]
	s_nop 0
	v_mov_b32_dpp v174, v163 row_ror:1 row_mask:0xf bank_mask:0xf
	v_mov_b32_e32 v163, v211
	s_nop 1
	v_mov_b32_dpp v163, v144 row_ror:2 row_mask:0xf bank_mask:0xf
	v_cndmask_b32_e64 v144, v149, v145, s[4:5]
	v_cndmask_b32_e64 v145, v145, v149, s[0:1]
	s_nop 0
	v_mov_b32_dpp v175, v144 row_ror:1 row_mask:0xf bank_mask:0xf
	v_mov_b32_dpp v176, v145 row_ror:2 row_mask:0xf bank_mask:0xf
	v_cndmask_b32_e64 v144, v150, v146, s[4:5]
	v_cndmask_b32_e64 v145, v146, v150, s[0:1]
	s_nop 0
	v_mov_b32_dpp v177, v144 row_ror:1 row_mask:0xf bank_mask:0xf
	v_mov_b32_dpp v178, v145 row_ror:2 row_mask:0xf bank_mask:0xf
	v_cndmask_b32_e64 v144, v151, v147, s[4:5]
	v_cndmask_b32_e64 v145, v147, v151, s[0:1]
	v_pk_mul_f32 v[146:147], v[36:37], v[168:169]
	v_mov_b32_dpp v179, v144 row_ror:1 row_mask:0xf bank_mask:0xf
	v_mov_b32_dpp v180, v145 row_ror:2 row_mask:0xf bank_mask:0xf
	v_lshlrev_b32_e32 v145, 16, v174
	v_lshlrev_b32_e32 v144, 16, v148
	v_lshlrev_b32_e32 v168, 16, v163
	v_pk_mul_f32 v[144:145], v[156:157], v[144:145]
	v_and_b32_e32 v163, 0xffff0000, v163
	v_fma_f32 v145, v136, v168, v145
	v_add_f32_e32 v168, v144, v145
	v_and_b32_e32 v145, 0xffff0000, v174
	v_and_b32_e32 v144, 0xffff0000, v148
	v_pk_mul_f32 v[144:145], v[140:141], v[144:145]
	v_lshlrev_b32_e32 v169, 16, v176
	v_fma_f32 v145, v137, v163, v145
	v_add_f32_e32 v163, v144, v145
	v_lshlrev_b32_e32 v145, 16, v175
	v_lshlrev_b32_e32 v144, 16, v149
	v_pk_mul_f32 v[144:145], v[152:153], v[144:145]
	v_and_b32_e32 v174, 0xffff0000, v176
	v_fma_f32 v145, v138, v169, v145
	v_add_f32_e32 v169, v144, v145
	v_and_b32_e32 v145, 0xffff0000, v175
	v_and_b32_e32 v144, 0xffff0000, v149
	v_pk_mul_f32 v[144:145], v[142:143], v[144:145]
	v_lshlrev_b32_e32 v175, 16, v178
	v_fma_f32 v145, v139, v174, v145
	v_add_f32_e32 v174, v144, v145
	v_lshlrev_b32_e32 v145, 16, v177
	v_lshlrev_b32_e32 v144, 16, v150
	v_pk_mul_f32 v[144:145], v[154:155], v[144:145]
	v_and_b32_e32 v176, 0xffff0000, v178
	v_fma_f32 v145, v112, v175, v145
	v_add_f32_e32 v175, v144, v145
	v_and_b32_e32 v145, 0xffff0000, v177
	v_and_b32_e32 v144, 0xffff0000, v150
	v_pk_mul_f32 v[144:145], v[116:117], v[144:145]
	v_lshlrev_b32_e32 v177, 16, v180
	v_fma_f32 v145, v113, v176, v145
	v_add_f32_e32 v176, v144, v145
	v_lshlrev_b32_e32 v145, 16, v179
	v_lshlrev_b32_e32 v144, 16, v151
	v_pk_mul_f32 v[144:145], v[158:159], v[144:145]
	v_and_b32_e32 v178, 0xffff0000, v180
	v_fma_f32 v145, v114, v177, v145
	v_add_f32_e32 v177, v144, v145
	v_and_b32_e32 v145, 0xffff0000, v179
	v_and_b32_e32 v144, 0xffff0000, v151
	v_pk_mul_f32 v[144:145], v[118:119], v[144:145]
	v_mul_f32_e32 v146, v146, v175
	v_fma_f32 v145, v115, v178, v145
	v_add_f32_e32 v178, v144, v145
	v_pk_mul_f32 v[144:145], v[44:45], v[164:165]
	v_lshlrev_b64 v[164:165], 12, v[172:173]
	v_mul_f32_e32 v144, v144, v168
	v_mul_f32_e32 v145, v145, v163
	v_cvt_pk_bf16_f32 v144, v144, v145
	v_mul_f32_e32 v145, v166, v169
	v_mul_f32_e32 v147, v147, v176
	v_lshl_add_u64 v[164:165], s[12:13], 0, v[164:165]
	v_mul_f32_e32 v163, v167, v174
	v_cvt_pk_bf16_f32 v145, v145, v163
	v_cvt_pk_bf16_f32 v146, v146, v147
	v_mul_f32_e32 v147, v170, v177
	v_lshl_add_u64 v[164:165], v[164:165], 0, v[160:161]
	v_mul_f32_e32 v163, v171, v178
	v_cvt_pk_bf16_f32 v147, v147, v163
	s_cmp_lg_u32 s32, 0
	s_cbranch_scc1 .Lls_mb5_w
	global_store_dwordx4 v[164:165], v[144:147], off offset:2048
	s_branch .Lls_mb5_j

.Lls_mb5_j:
	v_or_b32_e32 v172, 32, v162
	v_ashrrev_i32_e32 v173, 31, v172
	v_mul_f32_e32 v144, 0xbfb8aa3b, v24
	v_mul_f32_e32 v145, 0xbfb8aa3b, v25
	v_exp_f32_e32 v144, v144
	v_exp_f32_e32 v145, v145
	v_mul_f32_e32 v146, 0xbfb8aa3b, v26
	v_mul_f32_e32 v147, 0xbfb8aa3b, v27
	v_exp_f32_e32 v146, v146
	v_exp_f32_e32 v147, v147
	v_add_f32_e32 v144, 1.0, v144
	v_add_f32_e32 v145, 1.0, v145
	v_rcp_f32_e32 v144, v144
	v_rcp_f32_e32 v145, v145
	v_add_f32_e32 v146, 1.0, v146
	v_add_f32_e32 v147, 1.0, v147
	v_rcp_f32_e32 v146, v146
	v_rcp_f32_e32 v147, v147
	v_pk_mul_f32 v[164:165], v[24:25], v[144:145]
	v_mul_f32_e32 v144, 0xbfb8aa3b, v16
	v_mul_f32_e32 v145, 0xbfb8aa3b, v17
	v_exp_f32_e32 v144, v144
	v_exp_f32_e32 v145, v145
	v_pk_mul_f32 v[166:167], v[26:27], v[146:147]
	v_mul_f32_e32 v146, 0xbfb8aa3b, v18
	v_mul_f32_e32 v147, 0xbfb8aa3b, v19
	v_exp_f32_e32 v146, v146
	v_exp_f32_e32 v147, v147
	v_add_f32_e32 v144, 1.0, v144
	v_add_f32_e32 v145, 1.0, v145
	v_rcp_f32_e32 v144, v144
	v_rcp_f32_e32 v145, v145
	v_add_f32_e32 v146, 1.0, v146
	v_add_f32_e32 v147, 1.0, v147
	v_rcp_f32_e32 v146, v146
	v_rcp_f32_e32 v147, v147
	v_pk_mul_f32 v[168:169], v[16:17], v[144:145]
	v_lshlrev_b64 v[144:145], 11, v[172:173]
	v_lshl_add_u64 v[144:145], s[50:51], 0, v[144:145]
	v_lshl_add_u64 v[144:145], v[144:145], 0, v[160:161]
	v_pk_mul_f32 v[170:171], v[18:19], v[146:147]
	s_waitcnt vmcnt(6)
	v_mov_b32_e32 v144, v192
	v_mov_b32_e32 v145, v193
	v_mov_b32_e32 v146, v194
	v_mov_b32_e32 v147, v195
	v_mov_b32_e32 v174, v211
	v_mov_b32_e32 v175, v211
	v_mov_b32_e32 v176, v211
	v_mov_b32_e32 v177, v211
	v_mov_b32_e32 v178, v211
	v_mov_b32_e32 v179, v211
	v_mov_b32_e32 v180, v211
	v_pk_mul_f32 v[166:167], v[30:31], v[166:167]
	v_pk_mul_f32 v[170:171], v[22:23], v[170:171]
	v_cndmask_b32_e64 v163, v144, v148, s[4:5]
	v_cndmask_b32_e64 v148, v148, v144, s[0:1]
	s_nop 0
	v_mov_b32_dpp v174, v163 row_ror:1 row_mask:0xf bank_mask:0xf
	v_mov_b32_e32 v163, v211
	s_nop 1
	v_mov_b32_dpp v163, v148 row_ror:2 row_mask:0xf bank_mask:0xf
	v_cndmask_b32_e64 v148, v145, v149, s[4:5]
	v_cndmask_b32_e64 v149, v149, v145, s[0:1]
	s_nop 0
	v_mov_b32_dpp v175, v148 row_ror:1 row_mask:0xf bank_mask:0xf
	v_mov_b32_dpp v176, v149 row_ror:2 row_mask:0xf bank_mask:0xf
	v_cndmask_b32_e64 v148, v146, v150, s[4:5]
	v_cndmask_b32_e64 v149, v150, v146, s[0:1]
	s_nop 0
	v_mov_b32_dpp v177, v148 row_ror:1 row_mask:0xf bank_mask:0xf
	v_mov_b32_dpp v178, v149 row_ror:2 row_mask:0xf bank_mask:0xf
	v_cndmask_b32_e64 v148, v147, v151, s[4:5]
	v_cndmask_b32_e64 v149, v151, v147, s[0:1]
	v_pk_mul_f32 v[150:151], v[20:21], v[168:169]
	v_mov_b32_dpp v179, v148 row_ror:1 row_mask:0xf bank_mask:0xf
	v_mov_b32_dpp v180, v149 row_ror:2 row_mask:0xf bank_mask:0xf
	v_lshlrev_b32_e32 v149, 16, v174
	v_lshlrev_b32_e32 v148, 16, v144
	v_lshlrev_b32_e32 v168, 16, v163
	v_pk_mul_f32 v[148:149], v[156:157], v[148:149]
	v_and_b32_e32 v163, 0xffff0000, v163
	v_fma_f32 v149, v136, v168, v149
	v_add_f32_e32 v168, v148, v149
	v_and_b32_e32 v149, 0xffff0000, v174
	v_and_b32_e32 v148, 0xffff0000, v144
	v_pk_mul_f32 v[148:149], v[140:141], v[148:149]
	v_lshlrev_b32_e32 v169, 16, v176
	v_fma_f32 v149, v137, v163, v149
	v_add_f32_e32 v163, v148, v149
	v_lshlrev_b32_e32 v149, 16, v175
	v_lshlrev_b32_e32 v148, 16, v145
	v_pk_mul_f32 v[148:149], v[152:153], v[148:149]
	v_and_b32_e32 v174, 0xffff0000, v176
	v_fma_f32 v149, v138, v169, v149
	v_add_f32_e32 v169, v148, v149
	v_and_b32_e32 v149, 0xffff0000, v175
	v_and_b32_e32 v148, 0xffff0000, v145
	v_pk_mul_f32 v[148:149], v[142:143], v[148:149]
	v_lshlrev_b32_e32 v175, 16, v178
	v_fma_f32 v149, v139, v174, v149
	v_add_f32_e32 v174, v148, v149
	v_lshlrev_b32_e32 v149, 16, v177
	v_lshlrev_b32_e32 v148, 16, v146
	v_pk_mul_f32 v[148:149], v[154:155], v[148:149]
	v_and_b32_e32 v176, 0xffff0000, v178
	v_fma_f32 v149, v112, v175, v149
	v_add_f32_e32 v175, v148, v149
	v_and_b32_e32 v149, 0xffff0000, v177
	v_and_b32_e32 v148, 0xffff0000, v146
	v_pk_mul_f32 v[148:149], v[116:117], v[148:149]
	v_lshlrev_b32_e32 v177, 16, v180
	v_fma_f32 v149, v113, v176, v149
	v_add_f32_e32 v176, v148, v149
	v_lshlrev_b32_e32 v149, 16, v179
	v_lshlrev_b32_e32 v148, 16, v147
	v_pk_mul_f32 v[148:149], v[158:159], v[148:149]
	v_and_b32_e32 v178, 0xffff0000, v180
	v_fma_f32 v149, v114, v177, v149
	v_add_f32_e32 v177, v148, v149
	v_and_b32_e32 v149, 0xffff0000, v179
	v_and_b32_e32 v148, 0xffff0000, v147
	v_pk_mul_f32 v[148:149], v[118:119], v[148:149]
	v_mul_f32_e32 v150, v150, v175
	v_fma_f32 v149, v115, v178, v149
	v_add_f32_e32 v178, v148, v149
	v_pk_mul_f32 v[148:149], v[28:29], v[164:165]
	v_mul_f32_e32 v151, v151, v176
	v_mul_f32_e32 v148, v148, v168
	v_mul_f32_e32 v149, v149, v163
	v_or_b32_e32 v168, 48, v162
	v_cvt_pk_bf16_f32 v148, v148, v149
	v_mul_f32_e32 v149, v166, v169
	v_mul_f32_e32 v163, v167, v174
	v_lshlrev_b64 v[164:165], 12, v[172:173]
	v_ashrrev_i32_e32 v169, 31, v168
	v_cvt_pk_bf16_f32 v149, v149, v163
	v_cvt_pk_bf16_f32 v150, v150, v151
	v_mul_f32_e32 v151, v170, v177
	v_mul_f32_e32 v163, v171, v178
	v_lshl_add_u64 v[164:165], s[12:13], 0, v[164:165]
	v_lshlrev_b64 v[170:171], 11, v[168:169]
	v_lshl_add_u64 v[164:165], v[164:165], 0, v[160:161]
	v_lshl_add_u64 v[170:171], s[50:51], 0, v[170:171]
	v_cvt_pk_bf16_f32 v151, v151, v163
	s_cmp_lg_u32 s32, 0
	s_cbranch_scc1 .Lls_mb6_w
	global_store_dwordx4 v[164:165], v[148:151], off offset:2048
	s_branch .Lls_mb6_j

.Lls_mb6_j:
	v_lshl_add_u64 v[170:171], v[170:171], 0, v[160:161]
	s_waitcnt vmcnt(5)
	v_mov_b32_e32 v170, v196
	v_mov_b32_e32 v171, v197
	v_mov_b32_e32 v172, v198
	v_mov_b32_e32 v173, v199
	v_mul_f32_e32 v163, 0xbfb8aa3b, v0
	v_exp_f32_e32 v163, v163
	v_mov_b32_e32 v174, v211
	v_mov_b32_e32 v175, v211
	v_mov_b32_e32 v176, v211
	v_add_f32_e32 v163, 1.0, v163
	v_rcp_f32_e32 v164, v163
	v_mul_f32_e32 v163, 0xbfb8aa3b, v1
	v_exp_f32_e32 v163, v163
	v_mov_b32_e32 v177, v211
	v_mov_b32_e32 v178, v211
	v_mov_b32_e32 v179, v211
	v_add_f32_e32 v163, 1.0, v163
	v_rcp_f32_e32 v165, v163
	v_mul_f32_e32 v163, 0xbfb8aa3b, v2
	v_exp_f32_e32 v163, v163
	v_mov_b32_e32 v180, v211
	v_mul_f32_e32 v148, 0xbfb8aa3b, v8
	v_mul_f32_e32 v149, 0xbfb8aa3b, v9
	v_add_f32_e32 v163, 1.0, v163
	v_rcp_f32_e32 v166, v163
	v_mul_f32_e32 v163, 0xbfb8aa3b, v3
	v_exp_f32_e32 v163, v163
	v_exp_f32_e32 v148, v148
	v_exp_f32_e32 v149, v149
	v_mul_f32_e32 v150, 0xbfb8aa3b, v10
	v_add_f32_e32 v163, 1.0, v163
	v_rcp_f32_e32 v167, v163
	v_mul_f32_e32 v151, 0xbfb8aa3b, v11
	v_exp_f32_e32 v150, v150
	v_exp_f32_e32 v151, v151
	v_add_f32_e32 v148, 1.0, v148
	v_add_f32_e32 v149, 1.0, v149
	v_rcp_f32_e32 v148, v148
	v_rcp_f32_e32 v149, v149
	v_add_f32_e32 v150, 1.0, v150
	v_add_f32_e32 v151, 1.0, v151
	v_rcp_f32_e32 v150, v150
	v_rcp_f32_e32 v151, v151
	v_pk_mul_f32 v[148:149], v[8:9], v[148:149]
	v_pk_mul_f32 v[164:165], v[0:1], v[164:165]
	v_pk_mul_f32 v[166:167], v[2:3], v[166:167]
	v_pk_mul_f32 v[150:151], v[10:11], v[150:151]
	v_pk_mul_f32 v[164:165], v[4:5], v[164:165]
	v_pk_mul_f32 v[166:167], v[6:7], v[166:167]
	v_cndmask_b32_e64 v163, v170, v144, s[4:5]
	v_cndmask_b32_e64 v144, v144, v170, s[0:1]
	s_nop 0
	v_mov_b32_dpp v174, v163 row_ror:1 row_mask:0xf bank_mask:0xf
	v_mov_b32_e32 v163, v211
	s_nop 1
	v_mov_b32_dpp v163, v144 row_ror:2 row_mask:0xf bank_mask:0xf
	v_cndmask_b32_e64 v144, v171, v145, s[4:5]
	v_cndmask_b32_e64 v145, v145, v171, s[0:1]
	v_lshlrev_b32_e32 v181, 16, v163
	v_mov_b32_dpp v175, v144 row_ror:1 row_mask:0xf bank_mask:0xf
	v_mov_b32_dpp v176, v145 row_ror:2 row_mask:0xf bank_mask:0xf
	v_cndmask_b32_e64 v144, v172, v146, s[4:5]
	v_cndmask_b32_e64 v145, v146, v172, s[0:1]
	s_nop 0
	v_mov_b32_dpp v177, v144 row_ror:1 row_mask:0xf bank_mask:0xf
	v_mov_b32_dpp v178, v145 row_ror:2 row_mask:0xf bank_mask:0xf
	v_cndmask_b32_e64 v144, v173, v147, s[4:5]
	v_cndmask_b32_e64 v145, v147, v173, s[0:1]
	s_nop 0
	v_mov_b32_dpp v179, v144 row_ror:1 row_mask:0xf bank_mask:0xf
	v_mov_b32_dpp v180, v145 row_ror:2 row_mask:0xf bank_mask:0xf
	v_lshlrev_b32_e32 v145, 16, v174
	v_lshlrev_b32_e32 v144, 16, v170
	v_pk_mul_f32 v[146:147], v[156:157], v[144:145]
	v_and_b32_e32 v157, 0xffff0000, v174
	v_fma_f32 v136, v136, v181, v147
	v_and_b32_e32 v156, 0xffff0000, v170
	v_add_f32_e32 v145, v146, v136
	v_and_b32_e32 v136, 0xffff0000, v163
	v_pk_mul_f32 v[140:141], v[140:141], v[156:157]
	v_lshlrev_b32_e32 v147, 16, v175
	v_fma_f32 v136, v137, v136, v141
	v_lshlrev_b32_e32 v146, 16, v171
	v_add_f32_e32 v157, v140, v136
	v_lshlrev_b32_e32 v140, 16, v176
	v_pk_mul_f32 v[136:137], v[152:153], v[146:147]
	v_and_b32_e32 v141, 0xffff0000, v175
	v_fma_f32 v137, v138, v140, v137
	v_and_b32_e32 v140, 0xffff0000, v171
	v_add_f32_e32 v147, v136, v137
	v_and_b32_e32 v138, 0xffff0000, v176
	v_pk_mul_f32 v[136:137], v[142:143], v[140:141]
	v_lshlrev_b32_e32 v142, 16, v178
	v_fma_f32 v137, v139, v138, v137
	v_add_f32_e32 v141, v136, v137
	v_lshlrev_b32_e32 v137, 16, v177
	v_lshlrev_b32_e32 v136, 16, v172
	v_pk_mul_f32 v[138:139], v[154:155], v[136:137]
	v_and_b32_e32 v143, 0xffff0000, v177
	v_fma_f32 v112, v112, v142, v139
	v_and_b32_e32 v142, 0xffff0000, v172
	v_add_f32_e32 v137, v138, v112
	v_and_b32_e32 v112, 0xffff0000, v178
	v_pk_mul_f32 v[116:117], v[116:117], v[142:143]
	v_lshlrev_b32_e32 v139, 16, v179
	v_fma_f32 v112, v113, v112, v117
	v_lshlrev_b32_e32 v138, 16, v173
	v_add_f32_e32 v143, v116, v112
	v_lshlrev_b32_e32 v116, 16, v180
	v_pk_mul_f32 v[112:113], v[158:159], v[138:139]
	s_nop 0
	v_fma_f32 v113, v114, v116, v113
	v_add_f32_e32 v139, v112, v113
	v_and_b32_e32 v113, 0xffff0000, v179
	v_and_b32_e32 v112, 0xffff0000, v173
	v_and_b32_e32 v114, 0xffff0000, v180
	v_pk_mul_f32 v[116:117], v[118:119], v[112:113]
	s_nop 0
	v_fma_f32 v113, v115, v114, v117
	v_pk_mul_f32 v[114:115], v[12:13], v[148:149]
	v_add_f32_e32 v118, v116, v113
	v_pk_mul_f32 v[116:117], v[14:15], v[150:151]
	v_mul_f32_e32 v114, v114, v145
	v_mul_f32_e32 v115, v115, v157
	v_cvt_pk_bf16_f32 v114, v114, v115
	v_mul_f32_e32 v115, v116, v147
	v_mul_f32_e32 v116, v117, v141
	v_cvt_pk_bf16_f32 v115, v115, v116
	v_mul_f32_e32 v116, v164, v137
	v_mul_f32_e32 v117, v165, v143
	v_cvt_pk_bf16_f32 v116, v116, v117
	v_mul_f32_e32 v117, v166, v139
	v_mul_f32_e32 v118, v167, v118
	v_cvt_pk_bf16_f32 v117, v117, v118
	v_lshlrev_b64 v[118:119], 12, v[168:169]
	v_bitop3_b32 v113, v162, s8, 48 bitop3:0xc8
	v_lshl_add_u64 v[118:119], s[12:13], 0, v[118:119]
	s_movk_i32 s8, 0x7fd
	v_lshl_add_u64 v[118:119], v[118:119], 0, v[160:161]
	v_cmp_lt_u32_e32 vcc, s8, v113
	s_cmp_lg_u32 s32, 0
	s_cbranch_scc1 .Lls_mb7_w
	global_store_dwordx4 v[118:119], v[114:117], off offset:2048
	s_branch .Lls_mb7_j
.Lls_mb7_w:
	global_store_dwordx4 v[118:119], v[114:117], off offset:2048 sc1
.Lls_mb7_j:
	s_and_saveexec_b64 s[8:9], vcc
	s_cbranch_execz .LBB0_320
	v_lshrrev_b32_e32 v114, 21, v169
	v_add_u32_e32 v114, v168, v114
	v_ashrrev_i32_e32 v114, 11, v114
	v_ashrrev_i32_e32 v115, 31, v114
	v_add_u32_e32 v116, 0xfffff802, v113
	v_mov_b32_e32 v117, v211
	v_lshlrev_b64 v[114:115], 13, v[114:115]
	v_lshl_add_u64 v[114:115], s[18:19], 0, v[114:115]
	v_lshlrev_b64 v[116:117], 12, v[116:117]
	v_lshl_add_u64 v[114:115], v[114:115], 0, v[116:117]
	v_lshl_add_u64 v[114:115], v[210:211], 2, v[114:115]
	v_mov_b32_e32 v145, v156
	v_mov_b32_e32 v147, v140
	v_mov_b32_e32 v137, v142
	v_mov_b32_e32 v139, v112
	global_store_dwordx4 v[114:115], v[144:147], off
	global_store_dwordx4 v[114:115], v[136:139], off offset:16
